# G3 epilogue: the eight row-scale LDS reads issued together at the top (register copies at the use sites, wait states behind stores)
# speedup vs baseline: 1.0056x; 1.0056x over previous
.LBB0_157:
	s_lshl_b32 s38, s79, 10
	s_and_b32 s38, s38, 0x400
	v_add_u32_e32 v161, s38, v158
	ds_read_b32 v244, v161
	ds_read_b32 v245, v161 offset:64
	ds_read_b32 v246, v161 offset:128
	ds_read_b32 v247, v161 offset:192
	ds_read_b32 v248, v161 offset:512
	ds_read_b32 v249, v161 offset:576
	ds_read_b32 v250, v161 offset:640
	ds_read_b32 v251, v161 offset:704
	v_lshl_add_u32 v154, s78, 8, v156
	s_lshl_b32 s38, s77, 8
	v_ashrrev_i32_e32 v155, 31, v154
	s_ashr_i32 s39, s38, 31
	v_lshlrev_b64 v[164:165], 13, v[154:155]
	v_lshl_add_u64 v[164:165], s[30:31], 0, v[164:165]
	s_lshl_b64 s[38:39], s[38:39], 1
	v_lshl_add_u64 v[164:165], v[164:165], 0, s[38:39]
	s_waitcnt lgkmcnt(0)
	v_mov_b32_e32 v162, v244
	v_pk_mul_f32 v[136:137], v[136:137], v[162:163] op_sel_hi:[1,0]
	v_pk_mul_f32 v[134:135], v[134:135], v[162:163] op_sel_hi:[1,0]
	v_pk_mul_f32 v[132:133], v[132:133], v[162:163] op_sel_hi:[1,0]
	v_pk_mul_f32 v[130:131], v[130:131], v[162:163] op_sel_hi:[1,0]
	v_lshl_add_u64 v[164:165], v[164:165], 0, s[50:51]
	v_max_f32_e32 v137, 0, v137
	v_max_f32_e32 v136, 0, v136
	v_max_f32_e32 v135, 0, v135
	v_max_f32_e32 v134, 0, v134
	v_max_f32_e32 v133, 0, v133
	v_max_f32_e32 v132, 0, v132
	v_max_f32_e32 v131, 0, v131
	v_max_f32_e32 v130, 0, v130
	v_pk_mul_f32 v[124:125], v[124:125], v[162:163] op_sel_hi:[1,0]
	v_pk_mul_f32 v[122:123], v[122:123], v[162:163] op_sel_hi:[1,0]
	v_lshl_add_u64 v[164:165], v[164:165], 0, v[152:153]
	v_pk_mul_f32 v[136:137], v[136:137], v[136:137]
	v_pk_mul_f32 v[134:135], v[134:135], v[134:135]
	v_pk_mul_f32 v[166:167], v[132:133], v[132:133]
	v_pk_mul_f32 v[132:133], v[130:131], v[130:131]
	v_cvt_pk_bf16_f32 v130, v134, v135
	v_cvt_pk_bf16_f32 v131, v136, v137
	v_pk_mul_f32 v[128:129], v[128:129], v[162:163] op_sel_hi:[1,0]
	v_pk_mul_f32 v[126:127], v[126:127], v[162:163] op_sel_hi:[1,0]
	v_max_f32_e32 v125, 0, v125
	v_max_f32_e32 v124, 0, v124
	v_max_f32_e32 v123, 0, v123
	v_max_f32_e32 v122, 0, v122
	v_cvt_pk_bf16_f32 v132, v132, v133
	v_cvt_pk_bf16_f32 v133, v166, v167
	global_store_dwordx4 v[164:165], v[130:133], off
	v_max_f32_e32 v129, 0, v129
	v_max_f32_e32 v128, 0, v128
	v_max_f32_e32 v127, 0, v127
	v_max_f32_e32 v126, 0, v126
	v_pk_mul_f32 v[130:131], v[124:125], v[124:125]
	v_pk_mul_f32 v[124:125], v[122:123], v[122:123]
	v_pk_mul_f32 v[128:129], v[128:129], v[128:129]
	v_pk_mul_f32 v[126:127], v[126:127], v[126:127]
	s_and_b64 vcc, exec, s[40:41]
	v_cvt_pk_bf16_f32 v122, v126, v127
	v_cvt_pk_bf16_f32 v123, v128, v129
	v_cvt_pk_bf16_f32 v124, v124, v125
	v_cvt_pk_bf16_f32 v125, v130, v131
	global_store_dwordx4 v[164:165], v[122:125], off offset:256
	s_nop 2
	v_mov_b32_e32 v124, v245
	s_waitcnt lgkmcnt(0)
	v_pk_mul_f32 v[120:121], v[120:121], v[124:125] op_sel_hi:[1,0]
	v_or_b32_e32 v122, 16, v154
	v_ashrrev_i32_e32 v123, 31, v122
	v_lshlrev_b64 v[122:123], 13, v[122:123]
	v_lshl_add_u64 v[122:123], s[30:31], 0, v[122:123]
	v_lshl_add_u64 v[122:123], v[122:123], 0, s[38:39]
	v_pk_mul_f32 v[118:119], v[118:119], v[124:125] op_sel_hi:[1,0]
	v_pk_mul_f32 v[116:117], v[116:117], v[124:125] op_sel_hi:[1,0]
	v_pk_mul_f32 v[114:115], v[114:115], v[124:125] op_sel_hi:[1,0]
	v_lshl_add_u64 v[122:123], v[122:123], 0, s[50:51]
	v_max_f32_e32 v121, 0, v121
	v_max_f32_e32 v120, 0, v120
	v_max_f32_e32 v119, 0, v119
	v_max_f32_e32 v118, 0, v118
	v_max_f32_e32 v117, 0, v117
	v_max_f32_e32 v116, 0, v116
	v_max_f32_e32 v115, 0, v115
	v_max_f32_e32 v114, 0, v114
	v_pk_mul_f32 v[108:109], v[108:109], v[124:125] op_sel_hi:[1,0]
	v_pk_mul_f32 v[106:107], v[106:107], v[124:125] op_sel_hi:[1,0]
	v_lshl_add_u64 v[122:123], v[122:123], 0, v[152:153]
	v_pk_mul_f32 v[120:121], v[120:121], v[120:121]
	v_pk_mul_f32 v[118:119], v[118:119], v[118:119]
	v_pk_mul_f32 v[126:127], v[116:117], v[116:117]
	v_pk_mul_f32 v[116:117], v[114:115], v[114:115]
	v_cvt_pk_bf16_f32 v114, v118, v119
	v_cvt_pk_bf16_f32 v115, v120, v121
	v_pk_mul_f32 v[112:113], v[112:113], v[124:125] op_sel_hi:[1,0]
	v_pk_mul_f32 v[110:111], v[110:111], v[124:125] op_sel_hi:[1,0]
	v_max_f32_e32 v109, 0, v109
	v_max_f32_e32 v108, 0, v108
	v_max_f32_e32 v107, 0, v107
	v_max_f32_e32 v106, 0, v106
	v_cvt_pk_bf16_f32 v116, v116, v117
	v_cvt_pk_bf16_f32 v117, v126, v127
	global_store_dwordx4 v[122:123], v[114:117], off
	v_max_f32_e32 v113, 0, v113
	v_max_f32_e32 v112, 0, v112
	v_max_f32_e32 v111, 0, v111
	v_max_f32_e32 v110, 0, v110
	v_pk_mul_f32 v[114:115], v[108:109], v[108:109]
	v_pk_mul_f32 v[108:109], v[106:107], v[106:107]
	v_pk_mul_f32 v[112:113], v[112:113], v[112:113]
	v_pk_mul_f32 v[110:111], v[110:111], v[110:111]
	s_nop 0
	v_cvt_pk_bf16_f32 v106, v110, v111
	v_cvt_pk_bf16_f32 v107, v112, v113
	v_cvt_pk_bf16_f32 v108, v108, v109
	v_cvt_pk_bf16_f32 v109, v114, v115
	global_store_dwordx4 v[122:123], v[106:109], off offset:256
	s_nop 2
	v_mov_b32_e32 v108, v246
	s_waitcnt lgkmcnt(0)
	v_pk_mul_f32 v[104:105], v[104:105], v[108:109] op_sel_hi:[1,0]
	v_or_b32_e32 v106, 32, v154
	v_ashrrev_i32_e32 v107, 31, v106
	v_lshlrev_b64 v[106:107], 13, v[106:107]
	v_lshl_add_u64 v[106:107], s[30:31], 0, v[106:107]
	v_lshl_add_u64 v[106:107], v[106:107], 0, s[38:39]
	v_pk_mul_f32 v[102:103], v[102:103], v[108:109] op_sel_hi:[1,0]
	v_pk_mul_f32 v[100:101], v[100:101], v[108:109] op_sel_hi:[1,0]
	v_pk_mul_f32 v[98:99], v[98:99], v[108:109] op_sel_hi:[1,0]
	v_lshl_add_u64 v[106:107], v[106:107], 0, s[50:51]
	v_max_f32_e32 v105, 0, v105
	v_max_f32_e32 v104, 0, v104
	v_max_f32_e32 v103, 0, v103
	v_max_f32_e32 v102, 0, v102
	v_max_f32_e32 v101, 0, v101
	v_max_f32_e32 v100, 0, v100
	v_max_f32_e32 v99, 0, v99
	v_max_f32_e32 v98, 0, v98
	v_pk_mul_f32 v[92:93], v[92:93], v[108:109] op_sel_hi:[1,0]
	v_pk_mul_f32 v[90:91], v[90:91], v[108:109] op_sel_hi:[1,0]
	v_lshl_add_u64 v[106:107], v[106:107], 0, v[152:153]
	v_pk_mul_f32 v[104:105], v[104:105], v[104:105]
	v_pk_mul_f32 v[102:103], v[102:103], v[102:103]
	v_pk_mul_f32 v[110:111], v[100:101], v[100:101]
	v_pk_mul_f32 v[100:101], v[98:99], v[98:99]
	v_cvt_pk_bf16_f32 v98, v102, v103
	v_cvt_pk_bf16_f32 v99, v104, v105
	v_pk_mul_f32 v[96:97], v[96:97], v[108:109] op_sel_hi:[1,0]
	v_pk_mul_f32 v[94:95], v[94:95], v[108:109] op_sel_hi:[1,0]
	v_max_f32_e32 v93, 0, v93
	v_max_f32_e32 v92, 0, v92
	v_max_f32_e32 v91, 0, v91
	v_max_f32_e32 v90, 0, v90
	v_cvt_pk_bf16_f32 v100, v100, v101
	v_cvt_pk_bf16_f32 v101, v110, v111
	global_store_dwordx4 v[106:107], v[98:101], off
	v_max_f32_e32 v97, 0, v97
	v_max_f32_e32 v96, 0, v96
	v_max_f32_e32 v95, 0, v95
	v_max_f32_e32 v94, 0, v94
	v_pk_mul_f32 v[98:99], v[92:93], v[92:93]
	v_pk_mul_f32 v[92:93], v[90:91], v[90:91]
	v_pk_mul_f32 v[96:97], v[96:97], v[96:97]
	v_pk_mul_f32 v[94:95], v[94:95], v[94:95]
	s_nop 0
	v_cvt_pk_bf16_f32 v90, v94, v95
	v_cvt_pk_bf16_f32 v91, v96, v97
	v_cvt_pk_bf16_f32 v92, v92, v93
	v_cvt_pk_bf16_f32 v93, v98, v99
	global_store_dwordx4 v[106:107], v[90:93], off offset:256
	s_nop 2
	v_mov_b32_e32 v92, v247
	s_waitcnt lgkmcnt(0)
	v_pk_mul_f32 v[88:89], v[88:89], v[92:93] op_sel_hi:[1,0]
	v_or_b32_e32 v90, 48, v154
	v_ashrrev_i32_e32 v91, 31, v90
	v_lshlrev_b64 v[90:91], 13, v[90:91]
	v_lshl_add_u64 v[90:91], s[30:31], 0, v[90:91]
	v_lshl_add_u64 v[90:91], v[90:91], 0, s[38:39]
	v_pk_mul_f32 v[86:87], v[86:87], v[92:93] op_sel_hi:[1,0]
	v_pk_mul_f32 v[84:85], v[84:85], v[92:93] op_sel_hi:[1,0]
	v_pk_mul_f32 v[82:83], v[82:83], v[92:93] op_sel_hi:[1,0]
	v_lshl_add_u64 v[90:91], v[90:91], 0, s[50:51]
	v_max_f32_e32 v89, 0, v89
	v_max_f32_e32 v88, 0, v88
	v_max_f32_e32 v87, 0, v87
	v_max_f32_e32 v86, 0, v86
	v_max_f32_e32 v85, 0, v85
	v_max_f32_e32 v84, 0, v84
	v_max_f32_e32 v83, 0, v83
	v_max_f32_e32 v82, 0, v82
	v_pk_mul_f32 v[76:77], v[76:77], v[92:93] op_sel_hi:[1,0]
	v_pk_mul_f32 v[74:75], v[74:75], v[92:93] op_sel_hi:[1,0]
	v_lshl_add_u64 v[90:91], v[90:91], 0, v[152:153]
	v_pk_mul_f32 v[88:89], v[88:89], v[88:89]
	v_pk_mul_f32 v[86:87], v[86:87], v[86:87]
	v_pk_mul_f32 v[94:95], v[84:85], v[84:85]
	v_pk_mul_f32 v[84:85], v[82:83], v[82:83]
	v_cvt_pk_bf16_f32 v82, v86, v87
	v_cvt_pk_bf16_f32 v83, v88, v89
	v_pk_mul_f32 v[80:81], v[80:81], v[92:93] op_sel_hi:[1,0]
	v_pk_mul_f32 v[78:79], v[78:79], v[92:93] op_sel_hi:[1,0]
	v_max_f32_e32 v77, 0, v77
	v_max_f32_e32 v76, 0, v76
	v_max_f32_e32 v75, 0, v75
	v_max_f32_e32 v74, 0, v74
	v_cvt_pk_bf16_f32 v84, v84, v85
	v_cvt_pk_bf16_f32 v85, v94, v95
	global_store_dwordx4 v[90:91], v[82:85], off
	v_max_f32_e32 v81, 0, v81
	v_max_f32_e32 v80, 0, v80
	v_max_f32_e32 v79, 0, v79
	v_max_f32_e32 v78, 0, v78
	v_pk_mul_f32 v[82:83], v[76:77], v[76:77]
	v_pk_mul_f32 v[76:77], v[74:75], v[74:75]
	v_pk_mul_f32 v[80:81], v[80:81], v[80:81]
	v_pk_mul_f32 v[78:79], v[78:79], v[78:79]
	s_nop 0
	v_cvt_pk_bf16_f32 v74, v78, v79
	v_cvt_pk_bf16_f32 v75, v80, v81
	v_cvt_pk_bf16_f32 v76, v76, v77
	v_cvt_pk_bf16_f32 v77, v82, v83
	global_store_dwordx4 v[90:91], v[74:77], off offset:256
	s_nop 2
	v_mov_b32_e32 v76, v248
	s_waitcnt lgkmcnt(0)
	v_pk_mul_f32 v[72:73], v[72:73], v[76:77] op_sel_hi:[1,0]
	v_add_u32_e32 v74, 0x80, v154
	v_ashrrev_i32_e32 v75, 31, v74
	v_lshlrev_b64 v[74:75], 13, v[74:75]
	v_lshl_add_u64 v[74:75], s[30:31], 0, v[74:75]
	v_lshl_add_u64 v[74:75], v[74:75], 0, s[38:39]
	v_pk_mul_f32 v[70:71], v[70:71], v[76:77] op_sel_hi:[1,0]
	v_pk_mul_f32 v[68:69], v[68:69], v[76:77] op_sel_hi:[1,0]
	v_pk_mul_f32 v[66:67], v[66:67], v[76:77] op_sel_hi:[1,0]
	v_lshl_add_u64 v[74:75], v[74:75], 0, s[50:51]
	v_max_f32_e32 v73, 0, v73
	v_max_f32_e32 v72, 0, v72
	v_max_f32_e32 v71, 0, v71
	v_max_f32_e32 v70, 0, v70
	v_max_f32_e32 v69, 0, v69
	v_max_f32_e32 v68, 0, v68
	v_max_f32_e32 v67, 0, v67
	v_max_f32_e32 v66, 0, v66
	v_pk_mul_f32 v[60:61], v[60:61], v[76:77] op_sel_hi:[1,0]
	v_pk_mul_f32 v[58:59], v[58:59], v[76:77] op_sel_hi:[1,0]
	v_lshl_add_u64 v[74:75], v[74:75], 0, v[152:153]
	v_pk_mul_f32 v[72:73], v[72:73], v[72:73]
	v_pk_mul_f32 v[70:71], v[70:71], v[70:71]
	v_pk_mul_f32 v[78:79], v[68:69], v[68:69]
	v_pk_mul_f32 v[68:69], v[66:67], v[66:67]
	v_cvt_pk_bf16_f32 v66, v70, v71
	v_cvt_pk_bf16_f32 v67, v72, v73
	v_pk_mul_f32 v[64:65], v[64:65], v[76:77] op_sel_hi:[1,0]
	v_pk_mul_f32 v[62:63], v[62:63], v[76:77] op_sel_hi:[1,0]
	v_max_f32_e32 v61, 0, v61
	v_max_f32_e32 v60, 0, v60
	v_max_f32_e32 v59, 0, v59
	v_max_f32_e32 v58, 0, v58
	v_cvt_pk_bf16_f32 v68, v68, v69
	v_cvt_pk_bf16_f32 v69, v78, v79
	global_store_dwordx4 v[74:75], v[66:69], off
	v_max_f32_e32 v65, 0, v65
	v_max_f32_e32 v64, 0, v64
	v_max_f32_e32 v63, 0, v63
	v_max_f32_e32 v62, 0, v62
	v_pk_mul_f32 v[66:67], v[60:61], v[60:61]
	v_pk_mul_f32 v[60:61], v[58:59], v[58:59]
	v_pk_mul_f32 v[64:65], v[64:65], v[64:65]
	v_pk_mul_f32 v[62:63], v[62:63], v[62:63]
	s_nop 0
	v_cvt_pk_bf16_f32 v58, v62, v63
	v_cvt_pk_bf16_f32 v59, v64, v65
	v_cvt_pk_bf16_f32 v60, v60, v61
	v_cvt_pk_bf16_f32 v61, v66, v67
	global_store_dwordx4 v[74:75], v[58:61], off offset:256
	s_nop 2
	v_mov_b32_e32 v60, v249
	s_waitcnt lgkmcnt(0)
	v_pk_mul_f32 v[56:57], v[56:57], v[60:61] op_sel_hi:[1,0]
	v_add_u32_e32 v58, 0x90, v154
	v_ashrrev_i32_e32 v59, 31, v58
	v_lshlrev_b64 v[58:59], 13, v[58:59]
	v_lshl_add_u64 v[58:59], s[30:31], 0, v[58:59]
	v_lshl_add_u64 v[58:59], v[58:59], 0, s[38:39]
	v_pk_mul_f32 v[54:55], v[54:55], v[60:61] op_sel_hi:[1,0]
	v_pk_mul_f32 v[52:53], v[52:53], v[60:61] op_sel_hi:[1,0]
	v_pk_mul_f32 v[50:51], v[50:51], v[60:61] op_sel_hi:[1,0]
	v_lshl_add_u64 v[58:59], v[58:59], 0, s[50:51]
	v_max_f32_e32 v57, 0, v57
	v_max_f32_e32 v56, 0, v56
	v_max_f32_e32 v55, 0, v55
	v_max_f32_e32 v54, 0, v54
	v_max_f32_e32 v53, 0, v53
	v_max_f32_e32 v52, 0, v52
	v_max_f32_e32 v51, 0, v51
	v_max_f32_e32 v50, 0, v50
	v_pk_mul_f32 v[44:45], v[44:45], v[60:61] op_sel_hi:[1,0]
	v_pk_mul_f32 v[42:43], v[42:43], v[60:61] op_sel_hi:[1,0]
	v_lshl_add_u64 v[58:59], v[58:59], 0, v[152:153]
	v_pk_mul_f32 v[56:57], v[56:57], v[56:57]
	v_pk_mul_f32 v[54:55], v[54:55], v[54:55]
	v_pk_mul_f32 v[62:63], v[52:53], v[52:53]
	v_pk_mul_f32 v[52:53], v[50:51], v[50:51]
	v_cvt_pk_bf16_f32 v50, v54, v55
	v_cvt_pk_bf16_f32 v51, v56, v57
	v_pk_mul_f32 v[48:49], v[48:49], v[60:61] op_sel_hi:[1,0]
	v_pk_mul_f32 v[46:47], v[46:47], v[60:61] op_sel_hi:[1,0]
	v_max_f32_e32 v45, 0, v45
	v_max_f32_e32 v44, 0, v44
	v_max_f32_e32 v43, 0, v43
	v_max_f32_e32 v42, 0, v42
	v_cvt_pk_bf16_f32 v52, v52, v53
	v_cvt_pk_bf16_f32 v53, v62, v63
	global_store_dwordx4 v[58:59], v[50:53], off
	v_max_f32_e32 v49, 0, v49
	v_max_f32_e32 v48, 0, v48
	v_max_f32_e32 v47, 0, v47
	v_max_f32_e32 v46, 0, v46
	v_pk_mul_f32 v[50:51], v[44:45], v[44:45]
	v_pk_mul_f32 v[44:45], v[42:43], v[42:43]
	v_pk_mul_f32 v[48:49], v[48:49], v[48:49]
	v_pk_mul_f32 v[46:47], v[46:47], v[46:47]
	s_nop 0
	v_cvt_pk_bf16_f32 v42, v46, v47
	v_cvt_pk_bf16_f32 v43, v48, v49
	v_cvt_pk_bf16_f32 v44, v44, v45
	v_cvt_pk_bf16_f32 v45, v50, v51
	global_store_dwordx4 v[58:59], v[42:45], off offset:256
	s_nop 2
	v_mov_b32_e32 v44, v250
	s_waitcnt lgkmcnt(0)
	v_pk_mul_f32 v[40:41], v[40:41], v[44:45] op_sel_hi:[1,0]
	v_add_u32_e32 v42, 0xa0, v154
	v_ashrrev_i32_e32 v43, 31, v42
	v_lshlrev_b64 v[42:43], 13, v[42:43]
	v_lshl_add_u64 v[42:43], s[30:31], 0, v[42:43]
	v_lshl_add_u64 v[42:43], v[42:43], 0, s[38:39]
	v_pk_mul_f32 v[38:39], v[38:39], v[44:45] op_sel_hi:[1,0]
	v_pk_mul_f32 v[36:37], v[36:37], v[44:45] op_sel_hi:[1,0]
	v_pk_mul_f32 v[34:35], v[34:35], v[44:45] op_sel_hi:[1,0]
	v_lshl_add_u64 v[42:43], v[42:43], 0, s[50:51]
	v_max_f32_e32 v41, 0, v41
	v_max_f32_e32 v40, 0, v40
	v_max_f32_e32 v39, 0, v39
	v_max_f32_e32 v38, 0, v38
	v_max_f32_e32 v37, 0, v37
	v_max_f32_e32 v36, 0, v36
	v_max_f32_e32 v35, 0, v35
	v_max_f32_e32 v34, 0, v34
	v_pk_mul_f32 v[28:29], v[28:29], v[44:45] op_sel_hi:[1,0]
	v_pk_mul_f32 v[26:27], v[26:27], v[44:45] op_sel_hi:[1,0]
	v_lshl_add_u64 v[42:43], v[42:43], 0, v[152:153]
	v_pk_mul_f32 v[40:41], v[40:41], v[40:41]
	v_pk_mul_f32 v[38:39], v[38:39], v[38:39]
	v_pk_mul_f32 v[46:47], v[36:37], v[36:37]
	v_pk_mul_f32 v[36:37], v[34:35], v[34:35]
	v_cvt_pk_bf16_f32 v34, v38, v39
	v_cvt_pk_bf16_f32 v35, v40, v41
	v_pk_mul_f32 v[32:33], v[32:33], v[44:45] op_sel_hi:[1,0]
	v_pk_mul_f32 v[30:31], v[30:31], v[44:45] op_sel_hi:[1,0]
	v_max_f32_e32 v29, 0, v29
	v_max_f32_e32 v28, 0, v28
	v_max_f32_e32 v27, 0, v27
	v_max_f32_e32 v26, 0, v26
	v_cvt_pk_bf16_f32 v36, v36, v37
	v_cvt_pk_bf16_f32 v37, v46, v47
	global_store_dwordx4 v[42:43], v[34:37], off
	v_max_f32_e32 v33, 0, v33
	v_max_f32_e32 v32, 0, v32
	v_max_f32_e32 v31, 0, v31
	v_max_f32_e32 v30, 0, v30
	v_pk_mul_f32 v[34:35], v[28:29], v[28:29]
	v_pk_mul_f32 v[28:29], v[26:27], v[26:27]
	v_pk_mul_f32 v[32:33], v[32:33], v[32:33]
	v_pk_mul_f32 v[30:31], v[30:31], v[30:31]
	s_nop 0
	v_cvt_pk_bf16_f32 v26, v30, v31
	v_cvt_pk_bf16_f32 v27, v32, v33
	v_cvt_pk_bf16_f32 v28, v28, v29
	v_cvt_pk_bf16_f32 v29, v34, v35
	global_store_dwordx4 v[42:43], v[26:29], off offset:256
	s_nop 2
	v_mov_b32_e32 v28, v251
	s_waitcnt lgkmcnt(0)
	v_pk_mul_f32 v[24:25], v[24:25], v[28:29] op_sel_hi:[1,0]
	v_add_u32_e32 v26, 0xb0, v154
	v_ashrrev_i32_e32 v27, 31, v26
	v_lshlrev_b64 v[26:27], 13, v[26:27]
	v_lshl_add_u64 v[26:27], s[30:31], 0, v[26:27]
	v_lshl_add_u64 v[26:27], v[26:27], 0, s[38:39]
	v_pk_mul_f32 v[22:23], v[22:23], v[28:29] op_sel_hi:[1,0]
	v_pk_mul_f32 v[20:21], v[20:21], v[28:29] op_sel_hi:[1,0]
	v_pk_mul_f32 v[18:19], v[18:19], v[28:29] op_sel_hi:[1,0]
	v_lshl_add_u64 v[26:27], v[26:27], 0, s[50:51]
	v_max_f32_e32 v25, 0, v25
	v_max_f32_e32 v24, 0, v24
	v_max_f32_e32 v23, 0, v23
	v_max_f32_e32 v22, 0, v22
	v_max_f32_e32 v21, 0, v21
	v_max_f32_e32 v20, 0, v20
	v_max_f32_e32 v19, 0, v19
	v_max_f32_e32 v18, 0, v18
	v_pk_mul_f32 v[12:13], v[12:13], v[28:29] op_sel_hi:[1,0]
	v_pk_mul_f32 v[10:11], v[10:11], v[28:29] op_sel_hi:[1,0]
	v_lshl_add_u64 v[26:27], v[26:27], 0, v[152:153]
	v_pk_mul_f32 v[24:25], v[24:25], v[24:25]
	v_pk_mul_f32 v[22:23], v[22:23], v[22:23]
	v_pk_mul_f32 v[30:31], v[20:21], v[20:21]
	v_pk_mul_f32 v[20:21], v[18:19], v[18:19]
	v_cvt_pk_bf16_f32 v18, v22, v23
	v_cvt_pk_bf16_f32 v19, v24, v25
	v_pk_mul_f32 v[16:17], v[16:17], v[28:29] op_sel_hi:[1,0]
	v_pk_mul_f32 v[14:15], v[14:15], v[28:29] op_sel_hi:[1,0]
	v_max_f32_e32 v13, 0, v13
	v_max_f32_e32 v12, 0, v12
	v_max_f32_e32 v11, 0, v11
	v_max_f32_e32 v10, 0, v10
	v_cvt_pk_bf16_f32 v20, v20, v21
	v_cvt_pk_bf16_f32 v21, v30, v31
	global_store_dwordx4 v[26:27], v[18:21], off
	v_max_f32_e32 v17, 0, v17
	v_max_f32_e32 v16, 0, v16
	v_max_f32_e32 v15, 0, v15
	v_max_f32_e32 v14, 0, v14
	v_pk_mul_f32 v[18:19], v[12:13], v[12:13]
	v_pk_mul_f32 v[12:13], v[10:11], v[10:11]
	v_pk_mul_f32 v[16:17], v[16:17], v[16:17]
	v_pk_mul_f32 v[14:15], v[14:15], v[14:15]
	s_mov_b64 s[38:39], -1
	v_cvt_pk_bf16_f32 v10, v14, v15
	v_cvt_pk_bf16_f32 v11, v16, v17
	v_cvt_pk_bf16_f32 v12, v12, v13
	v_cvt_pk_bf16_f32 v13, v18, v19
	global_store_dwordx4 v[26:27], v[10:13], off offset:256
	s_cbranch_vccnz .LBB0_144
	s_waitcnt vmcnt(0)
	v_add_f32_e32 v10, v6, v7
	v_add_f32_e32 v11, v8, v9
	v_add_f32_e32 v10, v10, v11
	v_add_f32_e32 v11, v2, v3
	v_add_f32_e32 v12, v4, v5
	v_add_f32_e32 v11, v11, v12
	v_add_f32_e32 v10, v11, v10
	ds_bpermute_b32 v11, v1, v10
	s_and_saveexec_b64 s[38:39], s[36:37]
	s_cbranch_execz .LBB0_160
	s_waitcnt lgkmcnt(0)
	v_add_f32_e32 v10, v10, v11
	v_fmamk_f32 v10, v10, 0x3a800000, v220
	v_rsq_f32_e32 v10, v10
	s_lshl_b32 s40, s76, 10
	s_and_b32 s40, s40, 0x400
	v_add_u32_e32 v11, s40, v159
	ds_write_b32 v11, v10
